# block attention loops: shorter row-max chain, persistent LDS fragment addresses shared by tile pairs, rescale threshold and bias kept in registers
# speedup vs baseline: 1.0103x; 1.0035x over previous
.Lmob_pk8:
.Lmob_pk14:
	v_add_u32_e32 v216, v166, v165
	v_add_u32_e32 v217, v167, v165
	v_add_u32_e32 v218, v168, v165
	v_add_u32_e32 v219, v169, v165
	v_add_u32_e32 v220, v170, v171
	v_add_u32_e32 v221, v170, v172
	v_mov_b32_e32 v123, 0xff800000
	v_mov_b32_e32 v177, v216
	v_mov_b32_e32 v178, v217
	v_mov_b32_e32 v179, v218
	v_mov_b32_e32 v180, v219
	v_add_f32_e32 v184, 0x42317218, v176
	v_mul_f32_e32 v185, 0xbe38aa3b, v176
	s_cmp_eq_u32 s49, 8
	s_cbranch_scc1 .Lmob_pw7
	s_waitcnt vmcnt(11)
	s_branch .Lmob_pbar

.Lmob_bar_e:
	s_barrier
	s_cmp_gt_i32 s69, s68
	s_cbranch_scc1 .Lmob_next_e
	s_and_b32 s40, s69, 15
	s_lshl_b32 s40, s40, 13
	s_cmp_eq_u32 s69, s68
	s_cbranch_scc1 .Lmob_last_e
	s_add_i32 s41, s69, 1
	s_and_b32 s41, s41, 15
	s_lshl_b32 s41, s41, 13
	s_cmp_lt_u32 s69, s67
	s_cbranch_scc1 .Lmob_lane_e
	ds_read_b128 v[66:69], v177 offset:8192
	ds_read_b128 v[70:73], v178 offset:8192
	ds_read_b128 v[74:77], v179 offset:8192
	ds_read_b128 v[78:81], v180 offset:8192
	v_add_u32_e32 v181, s40, v220
	v_add_u32_e32 v182, s40, v221
	ds_read_b128 v[104:107], v181 offset:4096
	ds_read_b128 v[108:111], v181 offset:6144
	ds_read_b128 v[112:115], v182 offset:4096
	ds_read_b128 v[116:119], v182 offset:6144
	v_max3_f32 v99, v34, v35, v36
	v_max3_f32 v99, v99, v37, v38
	v_max3_f32 v99, v99, v39, v40
	v_max3_f32 v99, v99, v41, v42
	v_max3_f32 v99, v99, v43, v44
	v_max3_f32 v99, v99, v45, v46
	v_max3_f32 v99, v99, v47, v48
	v_max_f32_e32 v99, v99, v49
	s_waitcnt lgkmcnt(4)
	v_mfma_f32_32x32x16_bf16 v[200:215], v[66:69], v[82:85], 0
	v_mov_b32_e32 v100, v99
	s_nop 1
	v_permlane32_swap_b32_e32 v99, v100
	v_max_f32_e32 v99, v99, v100
	v_mfma_f32_32x32x16_bf16 v[200:215], v[70:73], v[86:89], v[200:215]
	v_cmp_gt_f32_e32 vcc, v99, v184
	s_cbranch_vccnz .Lmob_rare_fbe
.Lmob_back_fbe:
	s_waitcnt lgkmcnt(0)
	v_add_u32_e32 v102, 1, v145
	v_med3_i32 v102, v102, 0, 24
	v_bfm_b32 v102, v102, 0
	v_fmamk_f32 v34, v34, 0x3e38aa3b, v185
	v_fmamk_f32 v35, v35, 0x3e38aa3b, v185
	v_fmamk_f32 v36, v36, 0x3e38aa3b, v185
	v_fmamk_f32 v37, v37, 0x3e38aa3b, v185
	v_fmamk_f32 v38, v38, 0x3e38aa3b, v185
	v_fmamk_f32 v39, v39, 0x3e38aa3b, v185
	v_fmamk_f32 v40, v40, 0x3e38aa3b, v185
	v_fmamk_f32 v41, v41, 0x3e38aa3b, v185
	v_mfma_f32_32x32x16_bf16 v[200:215], v[74:77], v[90:93], v[200:215]
	v_exp_f32_e32 v34, v34
	v_exp_f32_e32 v35, v35
	v_exp_f32_e32 v36, v36
	v_exp_f32_e32 v37, v37
	v_exp_f32_e32 v38, v38
	v_exp_f32_e32 v39, v39
	v_exp_f32_e32 v40, v40
	v_exp_f32_e32 v41, v41
	v_bfe_i32 v244, v102, 0, 1
	v_bfe_i32 v245, v102, 1, 1
	v_bfe_i32 v246, v102, 2, 1
	v_bfe_i32 v247, v102, 3, 1
	v_mfma_f32_32x32x16_bf16 v[200:215], v[78:81], v[94:97], v[200:215]
	v_bfe_i32 v248, v102, 4, 1
	v_bfe_i32 v249, v102, 5, 1
	v_bfe_i32 v250, v102, 6, 1
	v_bfe_i32 v251, v102, 7, 1
	v_and_b32_e32 v34, v244, v34
	v_and_b32_e32 v35, v245, v35
	v_and_b32_e32 v36, v246, v36
	v_and_b32_e32 v37, v247, v37
	v_and_b32_e32 v38, v248, v38
	v_and_b32_e32 v39, v249, v39
	v_and_b32_e32 v40, v250, v40
	v_and_b32_e32 v41, v251, v41
	v_add_f32_e32 v101, v34, v35
	v_add_f32_e32 v101, v101, v36
	v_add_f32_e32 v101, v101, v37
	v_add_f32_e32 v101, v101, v38
	v_add_f32_e32 v101, v101, v39
	v_add_f32_e32 v101, v101, v40
	v_add_f32_e32 v101, v101, v41
	v_cvt_pk_bf16_f32 v224, v34, v35
	v_cvt_pk_bf16_f32 v225, v36, v37
	v_cvt_pk_bf16_f32 v226, v38, v39
	v_cvt_pk_bf16_f32 v227, v40, v41
	v_fmamk_f32 v42, v42, 0x3e38aa3b, v185
	v_fmamk_f32 v43, v43, 0x3e38aa3b, v185
	v_mfma_f32_32x32x16_bf16 v[18:33], v[104:107], v[224:227], v[18:33]
	v_fmamk_f32 v44, v44, 0x3e38aa3b, v185
	v_fmamk_f32 v45, v45, 0x3e38aa3b, v185
	v_fmamk_f32 v46, v46, 0x3e38aa3b, v185
	v_fmamk_f32 v47, v47, 0x3e38aa3b, v185
	v_fmamk_f32 v48, v48, 0x3e38aa3b, v185
	v_fmamk_f32 v49, v49, 0x3e38aa3b, v185
	v_exp_f32_e32 v42, v42
	v_exp_f32_e32 v43, v43
	v_exp_f32_e32 v44, v44
	v_exp_f32_e32 v45, v45
	v_exp_f32_e32 v46, v46
	v_exp_f32_e32 v47, v47
	v_mfma_f32_32x32x16_bf16 v[2:17], v[108:111], v[224:227], v[2:17]
	v_exp_f32_e32 v48, v48
	v_exp_f32_e32 v49, v49
	v_bfe_i32 v244, v102, 16, 1
	v_bfe_i32 v245, v102, 17, 1
	v_bfe_i32 v246, v102, 18, 1
	v_bfe_i32 v247, v102, 19, 1
	v_bfe_i32 v248, v102, 20, 1
	v_bfe_i32 v249, v102, 21, 1
	v_bfe_i32 v250, v102, 22, 1
	v_bfe_i32 v251, v102, 23, 1
	v_and_b32_e32 v42, v244, v42
	v_and_b32_e32 v43, v245, v43
	v_and_b32_e32 v44, v246, v44
	v_and_b32_e32 v45, v247, v45
	v_and_b32_e32 v46, v248, v46
	v_and_b32_e32 v47, v249, v47
	v_and_b32_e32 v48, v250, v48
	v_and_b32_e32 v49, v251, v49
	v_add_f32_e32 v101, v101, v42
	v_add_f32_e32 v101, v101, v43
	v_add_f32_e32 v101, v101, v44
	v_add_f32_e32 v101, v101, v45
	v_add_f32_e32 v101, v101, v46
	v_add_f32_e32 v101, v101, v47
	v_add_f32_e32 v101, v101, v48
	v_add_f32_e32 v101, v101, v49
	v_cvt_pk_bf16_f32 v228, v42, v43
	v_cvt_pk_bf16_f32 v229, v44, v45
	v_cvt_pk_bf16_f32 v230, v46, v47
	v_cvt_pk_bf16_f32 v231, v48, v49
	v_add_f32_e32 v141, v141, v101
	s_nop 0
	v_mfma_f32_32x32x16_bf16 v[18:33], v[112:115], v[228:231], v[18:33]
	v_mfma_f32_32x32x16_bf16 v[2:17], v[116:119], v[228:231], v[2:17]
	s_branch .Lmob_next_e
.Lmob_lane_e:
	ds_read_b128 v[66:69], v177 offset:8192
	ds_read_b128 v[70:73], v178 offset:8192
	ds_read_b128 v[74:77], v179 offset:8192
	ds_read_b128 v[78:81], v180 offset:8192
	v_add_u32_e32 v181, s40, v220
	v_add_u32_e32 v182, s40, v221
	ds_read_b128 v[104:107], v181 offset:4096
	ds_read_b128 v[108:111], v181 offset:6144
	ds_read_b128 v[112:115], v182 offset:4096
	ds_read_b128 v[116:119], v182 offset:6144
	v_max3_f32 v99, v34, v35, v36
	v_max3_f32 v99, v99, v37, v38
	v_max3_f32 v99, v99, v39, v40
	v_max3_f32 v99, v99, v41, v42
	v_max3_f32 v99, v99, v43, v44
	v_max3_f32 v99, v99, v45, v46
	v_max3_f32 v99, v99, v47, v48
	v_max_f32_e32 v99, v99, v49
	s_waitcnt lgkmcnt(4)
	v_mfma_f32_32x32x16_bf16 v[200:215], v[66:69], v[82:85], 0
	v_mov_b32_e32 v100, v99
	s_nop 1
	v_permlane32_swap_b32_e32 v99, v100
	v_max_f32_e32 v99, v99, v100
	v_mfma_f32_32x32x16_bf16 v[200:215], v[70:73], v[86:89], v[200:215]
	v_cmp_gt_f32_e32 vcc, v99, v184
	s_cbranch_vccnz .Lmob_rare_fle
.Lmob_back_fle:
	s_waitcnt lgkmcnt(0)
	s_lshr_b32 s41, s69, 3
	v_bfe_u32 v100, v143, s41, 1
	v_cmp_ne_u32_e32 vcc, 0, v100
	s_nop 1
	v_cndmask_b32_e32 v98, v123, v185, vcc
	v_fmamk_f32 v34, v34, 0x3e38aa3b, v98
	v_fmamk_f32 v35, v35, 0x3e38aa3b, v98
	v_fmamk_f32 v36, v36, 0x3e38aa3b, v98
	v_fmamk_f32 v37, v37, 0x3e38aa3b, v98
	v_fmamk_f32 v38, v38, 0x3e38aa3b, v98
	v_fmamk_f32 v39, v39, 0x3e38aa3b, v98
	v_fmamk_f32 v40, v40, 0x3e38aa3b, v98
	v_fmamk_f32 v41, v41, 0x3e38aa3b, v98
	v_mfma_f32_32x32x16_bf16 v[200:215], v[74:77], v[90:93], v[200:215]
	v_exp_f32_e32 v34, v34
	v_exp_f32_e32 v35, v35
	v_exp_f32_e32 v36, v36
	v_exp_f32_e32 v37, v37
	v_exp_f32_e32 v38, v38
	v_exp_f32_e32 v39, v39
	v_exp_f32_e32 v40, v40
	v_exp_f32_e32 v41, v41
	v_add_f32_e32 v101, v34, v35
	v_add_f32_e32 v101, v101, v36
	v_add_f32_e32 v101, v101, v37
	v_mfma_f32_32x32x16_bf16 v[200:215], v[78:81], v[94:97], v[200:215]
	v_add_f32_e32 v101, v101, v38
	v_add_f32_e32 v101, v101, v39
	v_add_f32_e32 v101, v101, v40
	v_add_f32_e32 v101, v101, v41
	v_cvt_pk_bf16_f32 v224, v34, v35
	v_cvt_pk_bf16_f32 v225, v36, v37
	v_cvt_pk_bf16_f32 v226, v38, v39
	v_cvt_pk_bf16_f32 v227, v40, v41
	v_fmamk_f32 v42, v42, 0x3e38aa3b, v98
	v_fmamk_f32 v43, v43, 0x3e38aa3b, v98
	v_mfma_f32_32x32x16_bf16 v[18:33], v[104:107], v[224:227], v[18:33]
	v_fmamk_f32 v44, v44, 0x3e38aa3b, v98
	v_fmamk_f32 v45, v45, 0x3e38aa3b, v98
	v_fmamk_f32 v46, v46, 0x3e38aa3b, v98
	v_fmamk_f32 v47, v47, 0x3e38aa3b, v98
	v_fmamk_f32 v48, v48, 0x3e38aa3b, v98
	v_fmamk_f32 v49, v49, 0x3e38aa3b, v98
	v_exp_f32_e32 v42, v42
	v_exp_f32_e32 v43, v43
	v_exp_f32_e32 v44, v44
	v_exp_f32_e32 v45, v45
	v_exp_f32_e32 v46, v46
	v_exp_f32_e32 v47, v47
	v_mfma_f32_32x32x16_bf16 v[2:17], v[108:111], v[224:227], v[2:17]
	v_exp_f32_e32 v48, v48
	v_exp_f32_e32 v49, v49
	v_add_f32_e32 v101, v101, v42
	v_add_f32_e32 v101, v101, v43
	v_add_f32_e32 v101, v101, v44
	v_add_f32_e32 v101, v101, v45
	v_add_f32_e32 v101, v101, v46
	v_add_f32_e32 v101, v101, v47
	v_add_f32_e32 v101, v101, v48
	v_add_f32_e32 v101, v101, v49
	v_cvt_pk_bf16_f32 v228, v42, v43
	v_cvt_pk_bf16_f32 v229, v44, v45
	v_cvt_pk_bf16_f32 v230, v46, v47
	v_cvt_pk_bf16_f32 v231, v48, v49
	v_add_f32_e32 v141, v141, v101
	s_nop 0
	v_mfma_f32_32x32x16_bf16 v[18:33], v[112:115], v[228:231], v[18:33]
	v_mfma_f32_32x32x16_bf16 v[2:17], v[116:119], v[228:231], v[2:17]
	s_branch .Lmob_next_e
.Lmob_last_e:
	v_add_u32_e32 v181, s40, v220
	v_add_u32_e32 v182, s40, v221
	ds_read_b128 v[104:107], v181 offset:4096
	ds_read_b128 v[108:111], v181 offset:6144
	ds_read_b128 v[112:115], v182 offset:4096
	ds_read_b128 v[116:119], v182 offset:6144
	v_max3_f32 v99, v34, v35, v36
	v_max3_f32 v99, v99, v37, v38
	v_max3_f32 v99, v99, v39, v40
	v_max3_f32 v99, v99, v41, v42
	v_max3_f32 v99, v99, v43, v44
	v_max3_f32 v99, v99, v45, v46
	v_max3_f32 v99, v99, v47, v48
	v_max_f32_e32 v99, v99, v49
	v_mov_b32_e32 v100, v99
	s_nop 1
	v_permlane32_swap_b32_e32 v99, v100
	v_max_f32_e32 v99, v99, v100
	v_cmp_gt_f32_e32 vcc, v99, v184
	s_cbranch_vccnz .Lmob_rare_lbe
.Lmob_back_lbe:
	s_waitcnt lgkmcnt(0)
	v_add_u32_e32 v102, 1, v145
	v_med3_i32 v102, v102, 0, 24
	v_bfm_b32 v102, v102, 0
	v_fmamk_f32 v34, v34, 0x3e38aa3b, v185
	v_fmamk_f32 v35, v35, 0x3e38aa3b, v185
	v_fmamk_f32 v36, v36, 0x3e38aa3b, v185
	v_fmamk_f32 v37, v37, 0x3e38aa3b, v185
	v_fmamk_f32 v38, v38, 0x3e38aa3b, v185
	v_fmamk_f32 v39, v39, 0x3e38aa3b, v185
	v_fmamk_f32 v40, v40, 0x3e38aa3b, v185
	v_fmamk_f32 v41, v41, 0x3e38aa3b, v185
	v_exp_f32_e32 v34, v34
	v_exp_f32_e32 v35, v35
	v_exp_f32_e32 v36, v36
	v_exp_f32_e32 v37, v37
	v_exp_f32_e32 v38, v38
	v_exp_f32_e32 v39, v39
	v_exp_f32_e32 v40, v40
	v_exp_f32_e32 v41, v41
	v_bfe_i32 v244, v102, 0, 1
	v_bfe_i32 v245, v102, 1, 1
	v_bfe_i32 v246, v102, 2, 1
	v_bfe_i32 v247, v102, 3, 1
	v_bfe_i32 v248, v102, 4, 1
	v_bfe_i32 v249, v102, 5, 1
	v_bfe_i32 v250, v102, 6, 1
	v_bfe_i32 v251, v102, 7, 1
	v_and_b32_e32 v34, v244, v34
	v_and_b32_e32 v35, v245, v35
	v_and_b32_e32 v36, v246, v36
	v_and_b32_e32 v37, v247, v37
	v_and_b32_e32 v38, v248, v38
	v_and_b32_e32 v39, v249, v39
	v_and_b32_e32 v40, v250, v40
	v_and_b32_e32 v41, v251, v41
	v_add_f32_e32 v101, v34, v35
	v_add_f32_e32 v101, v101, v36
	v_add_f32_e32 v101, v101, v37
	v_add_f32_e32 v101, v101, v38
	v_add_f32_e32 v101, v101, v39
	v_add_f32_e32 v101, v101, v40
	v_add_f32_e32 v101, v101, v41
	v_cvt_pk_bf16_f32 v224, v34, v35
	v_cvt_pk_bf16_f32 v225, v36, v37
	v_cvt_pk_bf16_f32 v226, v38, v39
	v_cvt_pk_bf16_f32 v227, v40, v41
	v_fmamk_f32 v42, v42, 0x3e38aa3b, v185
	v_fmamk_f32 v43, v43, 0x3e38aa3b, v185
	v_mfma_f32_32x32x16_bf16 v[18:33], v[104:107], v[224:227], v[18:33]
	v_fmamk_f32 v44, v44, 0x3e38aa3b, v185
	v_fmamk_f32 v45, v45, 0x3e38aa3b, v185
	v_fmamk_f32 v46, v46, 0x3e38aa3b, v185
	v_fmamk_f32 v47, v47, 0x3e38aa3b, v185
	v_fmamk_f32 v48, v48, 0x3e38aa3b, v185
	v_fmamk_f32 v49, v49, 0x3e38aa3b, v185
	v_exp_f32_e32 v42, v42
	v_exp_f32_e32 v43, v43
	v_exp_f32_e32 v44, v44
	v_exp_f32_e32 v45, v45
	v_exp_f32_e32 v46, v46
	v_exp_f32_e32 v47, v47
	v_mfma_f32_32x32x16_bf16 v[2:17], v[108:111], v[224:227], v[2:17]
	v_exp_f32_e32 v48, v48
	v_exp_f32_e32 v49, v49
	v_bfe_i32 v244, v102, 16, 1
	v_bfe_i32 v245, v102, 17, 1
	v_bfe_i32 v246, v102, 18, 1
	v_bfe_i32 v247, v102, 19, 1
	v_bfe_i32 v248, v102, 20, 1
	v_bfe_i32 v249, v102, 21, 1
	v_bfe_i32 v250, v102, 22, 1
	v_bfe_i32 v251, v102, 23, 1
	v_and_b32_e32 v42, v244, v42
	v_and_b32_e32 v43, v245, v43
	v_and_b32_e32 v44, v246, v44
	v_and_b32_e32 v45, v247, v45
	v_and_b32_e32 v46, v248, v46
	v_and_b32_e32 v47, v249, v47
	v_and_b32_e32 v48, v250, v48
	v_and_b32_e32 v49, v251, v49
	v_add_f32_e32 v101, v101, v42
	v_add_f32_e32 v101, v101, v43
	v_add_f32_e32 v101, v101, v44
	v_add_f32_e32 v101, v101, v45
	v_add_f32_e32 v101, v101, v46
	v_add_f32_e32 v101, v101, v47
	v_add_f32_e32 v101, v101, v48
	v_add_f32_e32 v101, v101, v49
	v_cvt_pk_bf16_f32 v228, v42, v43
	v_cvt_pk_bf16_f32 v229, v44, v45
	v_cvt_pk_bf16_f32 v230, v46, v47
	v_cvt_pk_bf16_f32 v231, v48, v49
	v_add_f32_e32 v141, v141, v101
	s_nop 0
	v_mfma_f32_32x32x16_bf16 v[18:33], v[112:115], v[228:231], v[18:33]
	v_mfma_f32_32x32x16_bf16 v[2:17], v[116:119], v[228:231], v[2:17]
	s_branch .Lmob_next_e

.Lmob_top_o:
	s_cmp_gt_i32 s69, s68
	s_cbranch_scc1 .Lmob_next_o
	s_and_b32 s40, s69, 15
	s_lshl_b32 s40, s40, 13
	s_cmp_eq_u32 s69, s68
	s_cbranch_scc1 .Lmob_last_o
	s_add_i32 s41, s69, 1
	s_and_b32 s41, s41, 15
	s_lshl_b32 s41, s41, 13
	s_cmp_lt_u32 s69, s67
	s_cbranch_scc1 .Lmob_lane_o
	v_add_u32_e32 v177, s41, v216
	ds_read_b128 v[66:69], v177
	v_add_u32_e32 v178, s41, v217
	ds_read_b128 v[70:73], v178
	v_add_u32_e32 v179, s41, v218
	ds_read_b128 v[74:77], v179
	v_add_u32_e32 v180, s41, v219
	ds_read_b128 v[78:81], v180
	ds_read_b128 v[104:107], v181 offset:12288
	ds_read_b128 v[108:111], v181 offset:14336
	ds_read_b128 v[112:115], v182 offset:12288
	ds_read_b128 v[116:119], v182 offset:14336
	v_max3_f32 v99, v200, v201, v202
	v_max3_f32 v99, v99, v203, v204
	v_max3_f32 v99, v99, v205, v206
	v_max3_f32 v99, v99, v207, v208
	v_max3_f32 v99, v99, v209, v210
	v_max3_f32 v99, v99, v211, v212
	v_max3_f32 v99, v99, v213, v214
	v_max_f32_e32 v99, v99, v215
	s_waitcnt lgkmcnt(4)
	v_mfma_f32_32x32x16_bf16 v[34:49], v[66:69], v[82:85], 0
	v_mov_b32_e32 v100, v99
	s_nop 1
	v_permlane32_swap_b32_e32 v99, v100
	v_max_f32_e32 v99, v99, v100
	v_mfma_f32_32x32x16_bf16 v[34:49], v[70:73], v[86:89], v[34:49]
	v_cmp_gt_f32_e32 vcc, v99, v184
	s_cbranch_vccnz .Lmob_rare_fbo
.Lmob_back_fbo:
	s_waitcnt lgkmcnt(0)
	v_add_u32_e32 v102, 1, v145
	v_med3_i32 v102, v102, 0, 24
	v_bfm_b32 v102, v102, 0
	v_fmamk_f32 v200, v200, 0x3e38aa3b, v185
	v_fmamk_f32 v201, v201, 0x3e38aa3b, v185
	v_fmamk_f32 v202, v202, 0x3e38aa3b, v185
	v_fmamk_f32 v203, v203, 0x3e38aa3b, v185
	v_fmamk_f32 v204, v204, 0x3e38aa3b, v185
	v_fmamk_f32 v205, v205, 0x3e38aa3b, v185
	v_fmamk_f32 v206, v206, 0x3e38aa3b, v185
	v_fmamk_f32 v207, v207, 0x3e38aa3b, v185
	v_mfma_f32_32x32x16_bf16 v[34:49], v[74:77], v[90:93], v[34:49]
	v_exp_f32_e32 v200, v200
	v_exp_f32_e32 v201, v201
	v_exp_f32_e32 v202, v202
	v_exp_f32_e32 v203, v203
	v_exp_f32_e32 v204, v204
	v_exp_f32_e32 v205, v205
	v_exp_f32_e32 v206, v206
	v_exp_f32_e32 v207, v207
	v_bfe_i32 v244, v102, 0, 1
	v_bfe_i32 v245, v102, 1, 1
	v_bfe_i32 v246, v102, 2, 1
	v_bfe_i32 v247, v102, 3, 1
	v_mfma_f32_32x32x16_bf16 v[34:49], v[78:81], v[94:97], v[34:49]
	v_bfe_i32 v248, v102, 4, 1
	v_bfe_i32 v249, v102, 5, 1
	v_bfe_i32 v250, v102, 6, 1
	v_bfe_i32 v251, v102, 7, 1
	v_and_b32_e32 v200, v244, v200
	v_and_b32_e32 v201, v245, v201
	v_and_b32_e32 v202, v246, v202
	v_and_b32_e32 v203, v247, v203
	v_and_b32_e32 v204, v248, v204
	v_and_b32_e32 v205, v249, v205
	v_and_b32_e32 v206, v250, v206
	v_and_b32_e32 v207, v251, v207
	v_add_f32_e32 v101, v200, v201
	v_add_f32_e32 v101, v101, v202
	v_add_f32_e32 v101, v101, v203
	v_add_f32_e32 v101, v101, v204
	v_add_f32_e32 v101, v101, v205
	v_add_f32_e32 v101, v101, v206
	v_add_f32_e32 v101, v101, v207
	v_cvt_pk_bf16_f32 v224, v200, v201
	v_cvt_pk_bf16_f32 v225, v202, v203
	v_cvt_pk_bf16_f32 v226, v204, v205
	v_cvt_pk_bf16_f32 v227, v206, v207
	v_fmamk_f32 v208, v208, 0x3e38aa3b, v185
	v_fmamk_f32 v209, v209, 0x3e38aa3b, v185
	v_mfma_f32_32x32x16_bf16 v[18:33], v[104:107], v[224:227], v[18:33]
	v_fmamk_f32 v210, v210, 0x3e38aa3b, v185
	v_fmamk_f32 v211, v211, 0x3e38aa3b, v185
	v_fmamk_f32 v212, v212, 0x3e38aa3b, v185
	v_fmamk_f32 v213, v213, 0x3e38aa3b, v185
	v_fmamk_f32 v214, v214, 0x3e38aa3b, v185
	v_fmamk_f32 v215, v215, 0x3e38aa3b, v185
	v_exp_f32_e32 v208, v208
	v_exp_f32_e32 v209, v209
	v_exp_f32_e32 v210, v210
	v_exp_f32_e32 v211, v211
	v_exp_f32_e32 v212, v212
	v_exp_f32_e32 v213, v213
	v_mfma_f32_32x32x16_bf16 v[2:17], v[108:111], v[224:227], v[2:17]
	v_exp_f32_e32 v214, v214
	v_exp_f32_e32 v215, v215
	v_bfe_i32 v244, v102, 16, 1
	v_bfe_i32 v245, v102, 17, 1
	v_bfe_i32 v246, v102, 18, 1
	v_bfe_i32 v247, v102, 19, 1
	v_bfe_i32 v248, v102, 20, 1
	v_bfe_i32 v249, v102, 21, 1
	v_bfe_i32 v250, v102, 22, 1
	v_bfe_i32 v251, v102, 23, 1
	v_and_b32_e32 v208, v244, v208
	v_and_b32_e32 v209, v245, v209
	v_and_b32_e32 v210, v246, v210
	v_and_b32_e32 v211, v247, v211
	v_and_b32_e32 v212, v248, v212
	v_and_b32_e32 v213, v249, v213
	v_and_b32_e32 v214, v250, v214
	v_and_b32_e32 v215, v251, v215
	v_add_f32_e32 v101, v101, v208
	v_add_f32_e32 v101, v101, v209
	v_add_f32_e32 v101, v101, v210
	v_add_f32_e32 v101, v101, v211
	v_add_f32_e32 v101, v101, v212
	v_add_f32_e32 v101, v101, v213
	v_add_f32_e32 v101, v101, v214
	v_add_f32_e32 v101, v101, v215
	v_cvt_pk_bf16_f32 v228, v208, v209
	v_cvt_pk_bf16_f32 v229, v210, v211
	v_cvt_pk_bf16_f32 v230, v212, v213
	v_cvt_pk_bf16_f32 v231, v214, v215
	v_add_f32_e32 v141, v141, v101
	s_nop 0
	v_mfma_f32_32x32x16_bf16 v[18:33], v[112:115], v[228:231], v[18:33]
	v_mfma_f32_32x32x16_bf16 v[2:17], v[116:119], v[228:231], v[2:17]
	s_branch .Lmob_next_o
.Lmob_lane_o:
	v_add_u32_e32 v177, s41, v216
	ds_read_b128 v[66:69], v177
	v_add_u32_e32 v178, s41, v217
	ds_read_b128 v[70:73], v178
	v_add_u32_e32 v179, s41, v218
	ds_read_b128 v[74:77], v179
	v_add_u32_e32 v180, s41, v219
	ds_read_b128 v[78:81], v180
	ds_read_b128 v[104:107], v181 offset:12288
	ds_read_b128 v[108:111], v181 offset:14336
	ds_read_b128 v[112:115], v182 offset:12288
	ds_read_b128 v[116:119], v182 offset:14336
	v_max3_f32 v99, v200, v201, v202
	v_max3_f32 v99, v99, v203, v204
	v_max3_f32 v99, v99, v205, v206
	v_max3_f32 v99, v99, v207, v208
	v_max3_f32 v99, v99, v209, v210
	v_max3_f32 v99, v99, v211, v212
	v_max3_f32 v99, v99, v213, v214
	v_max_f32_e32 v99, v99, v215
	s_waitcnt lgkmcnt(4)
	v_mfma_f32_32x32x16_bf16 v[34:49], v[66:69], v[82:85], 0
	v_mov_b32_e32 v100, v99
	s_nop 1
	v_permlane32_swap_b32_e32 v99, v100
	v_max_f32_e32 v99, v99, v100
	v_mfma_f32_32x32x16_bf16 v[34:49], v[70:73], v[86:89], v[34:49]
	v_cmp_gt_f32_e32 vcc, v99, v184
	s_cbranch_vccnz .Lmob_rare_flo
.Lmob_back_flo:
	s_waitcnt lgkmcnt(0)
	s_lshr_b32 s41, s69, 3
	v_bfe_u32 v100, v143, s41, 1
	v_cmp_ne_u32_e32 vcc, 0, v100
	s_nop 1
	v_cndmask_b32_e32 v98, v123, v185, vcc
	v_fmamk_f32 v200, v200, 0x3e38aa3b, v98
	v_fmamk_f32 v201, v201, 0x3e38aa3b, v98
	v_fmamk_f32 v202, v202, 0x3e38aa3b, v98
	v_fmamk_f32 v203, v203, 0x3e38aa3b, v98
	v_fmamk_f32 v204, v204, 0x3e38aa3b, v98
	v_fmamk_f32 v205, v205, 0x3e38aa3b, v98
	v_fmamk_f32 v206, v206, 0x3e38aa3b, v98
	v_fmamk_f32 v207, v207, 0x3e38aa3b, v98
	v_mfma_f32_32x32x16_bf16 v[34:49], v[74:77], v[90:93], v[34:49]
	v_exp_f32_e32 v200, v200
	v_exp_f32_e32 v201, v201
	v_exp_f32_e32 v202, v202
	v_exp_f32_e32 v203, v203
	v_exp_f32_e32 v204, v204
	v_exp_f32_e32 v205, v205
	v_exp_f32_e32 v206, v206
	v_exp_f32_e32 v207, v207
	v_add_f32_e32 v101, v200, v201
	v_add_f32_e32 v101, v101, v202
	v_add_f32_e32 v101, v101, v203
	v_mfma_f32_32x32x16_bf16 v[34:49], v[78:81], v[94:97], v[34:49]
	v_add_f32_e32 v101, v101, v204
	v_add_f32_e32 v101, v101, v205
	v_add_f32_e32 v101, v101, v206
	v_add_f32_e32 v101, v101, v207
	v_cvt_pk_bf16_f32 v224, v200, v201
	v_cvt_pk_bf16_f32 v225, v202, v203
	v_cvt_pk_bf16_f32 v226, v204, v205
	v_cvt_pk_bf16_f32 v227, v206, v207
	v_fmamk_f32 v208, v208, 0x3e38aa3b, v98
	v_fmamk_f32 v209, v209, 0x3e38aa3b, v98
	v_mfma_f32_32x32x16_bf16 v[18:33], v[104:107], v[224:227], v[18:33]
	v_fmamk_f32 v210, v210, 0x3e38aa3b, v98
	v_fmamk_f32 v211, v211, 0x3e38aa3b, v98
	v_fmamk_f32 v212, v212, 0x3e38aa3b, v98
	v_fmamk_f32 v213, v213, 0x3e38aa3b, v98
	v_fmamk_f32 v214, v214, 0x3e38aa3b, v98
	v_fmamk_f32 v215, v215, 0x3e38aa3b, v98
	v_exp_f32_e32 v208, v208
	v_exp_f32_e32 v209, v209
	v_exp_f32_e32 v210, v210
	v_exp_f32_e32 v211, v211
	v_exp_f32_e32 v212, v212
	v_exp_f32_e32 v213, v213
	v_mfma_f32_32x32x16_bf16 v[2:17], v[108:111], v[224:227], v[2:17]
	v_exp_f32_e32 v214, v214
	v_exp_f32_e32 v215, v215
	v_add_f32_e32 v101, v101, v208
	v_add_f32_e32 v101, v101, v209
	v_add_f32_e32 v101, v101, v210
	v_add_f32_e32 v101, v101, v211
	v_add_f32_e32 v101, v101, v212
	v_add_f32_e32 v101, v101, v213
	v_add_f32_e32 v101, v101, v214
	v_add_f32_e32 v101, v101, v215
	v_cvt_pk_bf16_f32 v228, v208, v209
	v_cvt_pk_bf16_f32 v229, v210, v211
	v_cvt_pk_bf16_f32 v230, v212, v213
	v_cvt_pk_bf16_f32 v231, v214, v215
	v_add_f32_e32 v141, v141, v101
	s_nop 0
	v_mfma_f32_32x32x16_bf16 v[18:33], v[112:115], v[228:231], v[18:33]
	v_mfma_f32_32x32x16_bf16 v[2:17], v[116:119], v[228:231], v[2:17]
	s_branch .Lmob_next_o
.Lmob_last_o:
	ds_read_b128 v[104:107], v181 offset:12288
	ds_read_b128 v[108:111], v181 offset:14336
	ds_read_b128 v[112:115], v182 offset:12288
	ds_read_b128 v[116:119], v182 offset:14336
	v_max3_f32 v99, v200, v201, v202
	v_max3_f32 v99, v99, v203, v204
	v_max3_f32 v99, v99, v205, v206
	v_max3_f32 v99, v99, v207, v208
	v_max3_f32 v99, v99, v209, v210
	v_max3_f32 v99, v99, v211, v212
	v_max3_f32 v99, v99, v213, v214
	v_max_f32_e32 v99, v99, v215
	v_mov_b32_e32 v100, v99
	s_nop 1
	v_permlane32_swap_b32_e32 v99, v100
	v_max_f32_e32 v99, v99, v100
	v_cmp_gt_f32_e32 vcc, v99, v184
	s_cbranch_vccnz .Lmob_rare_lbo
.Lmob_back_lbo:
	s_waitcnt lgkmcnt(0)
	v_add_u32_e32 v102, 1, v145
	v_med3_i32 v102, v102, 0, 24
	v_bfm_b32 v102, v102, 0
	v_fmamk_f32 v200, v200, 0x3e38aa3b, v185
	v_fmamk_f32 v201, v201, 0x3e38aa3b, v185
	v_fmamk_f32 v202, v202, 0x3e38aa3b, v185
	v_fmamk_f32 v203, v203, 0x3e38aa3b, v185
	v_fmamk_f32 v204, v204, 0x3e38aa3b, v185
	v_fmamk_f32 v205, v205, 0x3e38aa3b, v185
	v_fmamk_f32 v206, v206, 0x3e38aa3b, v185
	v_fmamk_f32 v207, v207, 0x3e38aa3b, v185
	v_exp_f32_e32 v200, v200
	v_exp_f32_e32 v201, v201
	v_exp_f32_e32 v202, v202
	v_exp_f32_e32 v203, v203
	v_exp_f32_e32 v204, v204
	v_exp_f32_e32 v205, v205
	v_exp_f32_e32 v206, v206
	v_exp_f32_e32 v207, v207
	v_bfe_i32 v244, v102, 0, 1
	v_bfe_i32 v245, v102, 1, 1
	v_bfe_i32 v246, v102, 2, 1
	v_bfe_i32 v247, v102, 3, 1
	v_bfe_i32 v248, v102, 4, 1
	v_bfe_i32 v249, v102, 5, 1
	v_bfe_i32 v250, v102, 6, 1
	v_bfe_i32 v251, v102, 7, 1
	v_and_b32_e32 v200, v244, v200
	v_and_b32_e32 v201, v245, v201
	v_and_b32_e32 v202, v246, v202
	v_and_b32_e32 v203, v247, v203
	v_and_b32_e32 v204, v248, v204
	v_and_b32_e32 v205, v249, v205
	v_and_b32_e32 v206, v250, v206
	v_and_b32_e32 v207, v251, v207
	v_add_f32_e32 v101, v200, v201
	v_add_f32_e32 v101, v101, v202
	v_add_f32_e32 v101, v101, v203
	v_add_f32_e32 v101, v101, v204
	v_add_f32_e32 v101, v101, v205
	v_add_f32_e32 v101, v101, v206
	v_add_f32_e32 v101, v101, v207
	v_cvt_pk_bf16_f32 v224, v200, v201
	v_cvt_pk_bf16_f32 v225, v202, v203
	v_cvt_pk_bf16_f32 v226, v204, v205
	v_cvt_pk_bf16_f32 v227, v206, v207
	v_fmamk_f32 v208, v208, 0x3e38aa3b, v185
	v_fmamk_f32 v209, v209, 0x3e38aa3b, v185
	v_mfma_f32_32x32x16_bf16 v[18:33], v[104:107], v[224:227], v[18:33]
	v_fmamk_f32 v210, v210, 0x3e38aa3b, v185
	v_fmamk_f32 v211, v211, 0x3e38aa3b, v185
	v_fmamk_f32 v212, v212, 0x3e38aa3b, v185
	v_fmamk_f32 v213, v213, 0x3e38aa3b, v185
	v_fmamk_f32 v214, v214, 0x3e38aa3b, v185
	v_fmamk_f32 v215, v215, 0x3e38aa3b, v185
	v_exp_f32_e32 v208, v208
	v_exp_f32_e32 v209, v209
	v_exp_f32_e32 v210, v210
	v_exp_f32_e32 v211, v211
	v_exp_f32_e32 v212, v212
	v_exp_f32_e32 v213, v213
	v_mfma_f32_32x32x16_bf16 v[2:17], v[108:111], v[224:227], v[2:17]
	v_exp_f32_e32 v214, v214
	v_exp_f32_e32 v215, v215
	v_bfe_i32 v244, v102, 16, 1
	v_bfe_i32 v245, v102, 17, 1
	v_bfe_i32 v246, v102, 18, 1
	v_bfe_i32 v247, v102, 19, 1
	v_bfe_i32 v248, v102, 20, 1
	v_bfe_i32 v249, v102, 21, 1
	v_bfe_i32 v250, v102, 22, 1
	v_bfe_i32 v251, v102, 23, 1
	v_and_b32_e32 v208, v244, v208
	v_and_b32_e32 v209, v245, v209
	v_and_b32_e32 v210, v246, v210
	v_and_b32_e32 v211, v247, v211
	v_and_b32_e32 v212, v248, v212
	v_and_b32_e32 v213, v249, v213
	v_and_b32_e32 v214, v250, v214
	v_and_b32_e32 v215, v251, v215
	v_add_f32_e32 v101, v101, v208
	v_add_f32_e32 v101, v101, v209
	v_add_f32_e32 v101, v101, v210
	v_add_f32_e32 v101, v101, v211
	v_add_f32_e32 v101, v101, v212
	v_add_f32_e32 v101, v101, v213
	v_add_f32_e32 v101, v101, v214
	v_add_f32_e32 v101, v101, v215
	v_cvt_pk_bf16_f32 v228, v208, v209
	v_cvt_pk_bf16_f32 v229, v210, v211
	v_cvt_pk_bf16_f32 v230, v212, v213
	v_cvt_pk_bf16_f32 v231, v214, v215
	v_add_f32_e32 v141, v141, v101
	s_nop 0
	v_mfma_f32_32x32x16_bf16 v[18:33], v[112:115], v[228:231], v[18:33]
	v_mfma_f32_32x32x16_bf16 v[2:17], v[116:119], v[228:231], v[2:17]
	s_branch .Lmob_next_o

.Lmob_rare_fbe:
	s_nop 15
	s_nop 15
	v_cndmask_b32_e32 v100, v176, v99, vcc
	v_sub_f32_e32 v120, v176, v100
	v_mul_f32_e32 v120, 0x3e38aa3b, v120
	v_exp_f32_e32 v120, v120
	v_mov_b32_e32 v176, v100
	v_add_f32_e32 v184, 0x42317218, v100
	v_mul_f32_e32 v185, 0xbe38aa3b, v100
	v_mul_f32_e32 v141, v141, v120
	v_pk_mul_f32 v[32:33], v[32:33], v[120:121] op_sel_hi:[1,0]
	v_pk_mul_f32 v[30:31], v[30:31], v[120:121] op_sel_hi:[1,0]
	v_pk_mul_f32 v[28:29], v[28:29], v[120:121] op_sel_hi:[1,0]
	v_pk_mul_f32 v[26:27], v[26:27], v[120:121] op_sel_hi:[1,0]
	v_pk_mul_f32 v[24:25], v[24:25], v[120:121] op_sel_hi:[1,0]
	v_pk_mul_f32 v[22:23], v[22:23], v[120:121] op_sel_hi:[1,0]
	v_pk_mul_f32 v[20:21], v[20:21], v[120:121] op_sel_hi:[1,0]
	v_pk_mul_f32 v[18:19], v[18:19], v[120:121] op_sel_hi:[1,0]
	v_pk_mul_f32 v[16:17], v[16:17], v[120:121] op_sel_hi:[1,0]
	v_pk_mul_f32 v[14:15], v[14:15], v[120:121] op_sel_hi:[1,0]
	v_pk_mul_f32 v[12:13], v[12:13], v[120:121] op_sel_hi:[1,0]
	v_pk_mul_f32 v[10:11], v[10:11], v[120:121] op_sel_hi:[1,0]
	v_pk_mul_f32 v[8:9], v[8:9], v[120:121] op_sel_hi:[1,0]
	v_pk_mul_f32 v[6:7], v[6:7], v[120:121] op_sel_hi:[1,0]
	v_pk_mul_f32 v[4:5], v[4:5], v[120:121] op_sel_hi:[1,0]
	v_pk_mul_f32 v[2:3], v[2:3], v[120:121] op_sel_hi:[1,0]
	s_branch .Lmob_back_fbe

.Ldsa_pk8:
	s_mov_b64 s[40:41], 0xc000
	v_lshl_add_u64 v[86:87], v[2:3], 0, s[40:41]
	s_add_i32 s53, s68, 7
	s_mov_b32 s65, 0
	v_mov_b32_e32 v0, 0
	v_mov_b64_e32 v[2:3], v[0:1]
	v_mov_b64_e32 v[4:5], v[0:1]
	v_mov_b64_e32 v[6:7], v[0:1]
	v_mov_b64_e32 v[8:9], v[0:1]
	v_mov_b64_e32 v[10:11], v[0:1]
	v_mov_b64_e32 v[12:13], v[0:1]
	v_mov_b64_e32 v[14:15], v[0:1]
	v_mov_b64_e32 v[16:17], v[0:1]
	v_mov_b64_e32 v[18:19], v[0:1]
	v_mov_b64_e32 v[20:21], v[0:1]
	v_mov_b64_e32 v[22:23], v[0:1]
	v_mov_b64_e32 v[24:25], v[0:1]
	v_mov_b64_e32 v[26:27], v[0:1]
	v_mov_b64_e32 v[28:29], v[0:1]
	v_mov_b64_e32 v[30:31], v[0:1]
	v_mov_b64_e32 v[32:33], v[0:1]
	v_mov_b32_e32 v83, 0xf149f2ca
	v_mov_b32_e32 v141, 0
	v_add_u32_e32 v216, v166, v165
	v_add_u32_e32 v217, v167, v165
	v_add_u32_e32 v218, v168, v165
	v_add_u32_e32 v219, v169, v165
	v_add_u32_e32 v220, v170, v171
	v_add_u32_e32 v221, v170, v172
	v_lshl_add_u32 v222, s1, 5, v135
	v_lshlrev_b32_e32 v222, 4, v222
	v_mov_b32_e32 v177, v216
	v_mov_b32_e32 v178, v217
	v_mov_b32_e32 v179, v218
	v_mov_b32_e32 v180, v219
	v_add_f32_e32 v184, 0x42317218, v83
	v_mul_f32_e32 v185, 0xbe38aa3b, v83
	s_cmp_eq_u32 s52, 8
	s_cbranch_scc1 .Ldsa_pw7
	s_waitcnt vmcnt(11)
	s_branch .Ldsa_pbar

.Ldsa_nomask:
	s_cmp_gt_i32 s65, s67
	s_cbranch_scc1 .Ldsa_next_e
	s_and_b32 s40, s65, 15
	s_lshl_b32 s40, s40, 13
	s_lshl_b32 s66, s65, 10
	s_and_b32 s66, s66, 0x3000
	s_and_b32 s41, s65, 3
	s_lshl_b32 s41, s41, 2
	s_add_i32 s66, s66, s41
	s_add_i32 s66, s66, 0x20020
	s_cmp_eq_u32 s65, s67
	s_cbranch_scc1 .Ldsa_last_e
	s_add_i32 s41, s65, 1
	s_and_b32 s41, s41, 15
	s_lshl_b32 s41, s41, 13
	ds_read_b128 v[66:69], v177 offset:8192
	ds_read_b128 v[70:73], v178 offset:8192
	ds_read_b128 v[74:77], v179 offset:8192
	ds_read_b128 v[78:81], v180 offset:8192
	v_add_u32_e32 v181, s40, v220
	v_add_u32_e32 v182, s40, v221
	ds_read_b128 v[104:107], v181 offset:4096
	ds_read_b128 v[108:111], v181 offset:6144
	ds_read_b128 v[112:115], v182 offset:4096
	ds_read_b128 v[116:119], v182 offset:6144
	v_add_u32_e32 v183, s66, v222
	ds_read_b32 v124, v183
	v_max3_f32 v121, v34, v35, v36
	v_max3_f32 v121, v121, v37, v38
	v_max3_f32 v121, v121, v39, v40
	v_max3_f32 v121, v121, v41, v42
	v_max3_f32 v121, v121, v43, v44
	v_max3_f32 v121, v121, v45, v46
	v_max3_f32 v121, v121, v47, v48
	v_max_f32_e32 v121, v121, v49
	s_waitcnt lgkmcnt(5)
	v_mfma_f32_32x32x16_bf16 v[200:215], v[66:69], v[50:53], 0
	v_mov_b32_e32 v122, v121
	s_nop 1
	v_permlane32_swap_b32_e32 v121, v122
	v_max_f32_e32 v121, v121, v122
	v_mfma_f32_32x32x16_bf16 v[200:215], v[70:73], v[54:57], v[200:215]
	v_cmp_gt_f32_e32 vcc, v121, v184
	s_cbranch_vccnz .Ldsa_rare_fbe
.Ldsa_back_fbe:
	s_waitcnt lgkmcnt(0)
	v_lshrrev_b32_e32 v124, v148, v124
	v_fmamk_f32 v34, v34, 0x3e38aa3b, v185
	v_fmamk_f32 v35, v35, 0x3e38aa3b, v185
	v_fmamk_f32 v36, v36, 0x3e38aa3b, v185
	v_fmamk_f32 v37, v37, 0x3e38aa3b, v185
	v_fmamk_f32 v38, v38, 0x3e38aa3b, v185
	v_fmamk_f32 v39, v39, 0x3e38aa3b, v185
	v_fmamk_f32 v40, v40, 0x3e38aa3b, v185
	v_fmamk_f32 v41, v41, 0x3e38aa3b, v185
	v_mfma_f32_32x32x16_bf16 v[200:215], v[74:77], v[58:61], v[200:215]
	v_exp_f32_e32 v34, v34
	v_exp_f32_e32 v35, v35
	v_exp_f32_e32 v36, v36
	v_exp_f32_e32 v37, v37
	v_exp_f32_e32 v38, v38
	v_exp_f32_e32 v39, v39
	v_exp_f32_e32 v40, v40
	v_exp_f32_e32 v41, v41
	v_bfe_i32 v96, v124, 0, 1
	v_bfe_i32 v97, v124, 1, 1
	v_bfe_i32 v98, v124, 2, 1
	v_bfe_i32 v99, v124, 3, 1
	v_mfma_f32_32x32x16_bf16 v[200:215], v[78:81], v[62:65], v[200:215]
	v_bfe_i32 v100, v124, 4, 1
	v_bfe_i32 v101, v124, 5, 1
	v_bfe_i32 v102, v124, 6, 1
	v_bfe_i32 v103, v124, 7, 1
	v_and_b32_e32 v34, v96, v34
	v_and_b32_e32 v35, v97, v35
	v_and_b32_e32 v36, v98, v36
	v_and_b32_e32 v37, v99, v37
	v_and_b32_e32 v38, v100, v38
	v_and_b32_e32 v39, v101, v39
	v_and_b32_e32 v40, v102, v40
	v_and_b32_e32 v41, v103, v41
	v_add_f32_e32 v123, v34, v35
	v_add_f32_e32 v123, v123, v36
	v_add_f32_e32 v123, v123, v37
	v_add_f32_e32 v123, v123, v38
	v_add_f32_e32 v123, v123, v39
	v_add_f32_e32 v123, v123, v40
	v_add_f32_e32 v123, v123, v41
	v_cvt_pk_bf16_f32 v88, v34, v35
	v_cvt_pk_bf16_f32 v89, v36, v37
	v_cvt_pk_bf16_f32 v90, v38, v39
	v_cvt_pk_bf16_f32 v91, v40, v41
	v_fmamk_f32 v42, v42, 0x3e38aa3b, v185
	v_fmamk_f32 v43, v43, 0x3e38aa3b, v185
	v_mfma_f32_32x32x16_bf16 v[18:33], v[104:107], v[88:91], v[18:33]
	v_fmamk_f32 v44, v44, 0x3e38aa3b, v185
	v_fmamk_f32 v45, v45, 0x3e38aa3b, v185
	v_fmamk_f32 v46, v46, 0x3e38aa3b, v185
	v_fmamk_f32 v47, v47, 0x3e38aa3b, v185
	v_fmamk_f32 v48, v48, 0x3e38aa3b, v185
	v_fmamk_f32 v49, v49, 0x3e38aa3b, v185
	v_exp_f32_e32 v42, v42
	v_exp_f32_e32 v43, v43
	v_exp_f32_e32 v44, v44
	v_exp_f32_e32 v45, v45
	v_exp_f32_e32 v46, v46
	v_exp_f32_e32 v47, v47
	v_mfma_f32_32x32x16_bf16 v[2:17], v[108:111], v[88:91], v[2:17]
	v_exp_f32_e32 v48, v48
	v_exp_f32_e32 v49, v49
	v_bfe_i32 v96, v124, 16, 1
	v_bfe_i32 v97, v124, 17, 1
	v_bfe_i32 v98, v124, 18, 1
	v_bfe_i32 v99, v124, 19, 1
	v_bfe_i32 v100, v124, 20, 1
	v_bfe_i32 v101, v124, 21, 1
	v_bfe_i32 v102, v124, 22, 1
	v_bfe_i32 v103, v124, 23, 1
	v_and_b32_e32 v42, v96, v42
	v_and_b32_e32 v43, v97, v43
	v_and_b32_e32 v44, v98, v44
	v_and_b32_e32 v45, v99, v45
	v_and_b32_e32 v46, v100, v46
	v_and_b32_e32 v47, v101, v47
	v_and_b32_e32 v48, v102, v48
	v_and_b32_e32 v49, v103, v49
	v_add_f32_e32 v123, v123, v42
	v_add_f32_e32 v123, v123, v43
	v_add_f32_e32 v123, v123, v44
	v_add_f32_e32 v123, v123, v45
	v_add_f32_e32 v123, v123, v46
	v_add_f32_e32 v123, v123, v47
	v_add_f32_e32 v123, v123, v48
	v_add_f32_e32 v123, v123, v49
	v_cvt_pk_bf16_f32 v92, v42, v43
	v_cvt_pk_bf16_f32 v93, v44, v45
	v_cvt_pk_bf16_f32 v94, v46, v47
	v_cvt_pk_bf16_f32 v95, v48, v49
	v_add_f32_e32 v141, v141, v123
	s_nop 0
	v_mfma_f32_32x32x16_bf16 v[18:33], v[112:115], v[92:95], v[18:33]
	v_mfma_f32_32x32x16_bf16 v[2:17], v[116:119], v[92:95], v[2:17]
	s_branch .Ldsa_next_e
.Ldsa_last_e:
	v_add_u32_e32 v181, s40, v220
	v_add_u32_e32 v182, s40, v221
	ds_read_b128 v[104:107], v181 offset:4096
	ds_read_b128 v[108:111], v181 offset:6144
	ds_read_b128 v[112:115], v182 offset:4096
	ds_read_b128 v[116:119], v182 offset:6144
	v_add_u32_e32 v183, s66, v222
	ds_read_b32 v124, v183
	v_max3_f32 v121, v34, v35, v36
	v_max3_f32 v121, v121, v37, v38
	v_max3_f32 v121, v121, v39, v40
	v_max3_f32 v121, v121, v41, v42
	v_max3_f32 v121, v121, v43, v44
	v_max3_f32 v121, v121, v45, v46
	v_max3_f32 v121, v121, v47, v48
	v_max_f32_e32 v121, v121, v49
	v_mov_b32_e32 v122, v121
	s_nop 1
	v_permlane32_swap_b32_e32 v121, v122
	v_max_f32_e32 v121, v121, v122
	v_cmp_gt_f32_e32 vcc, v121, v184
	s_cbranch_vccnz .Ldsa_rare_lbe
.Ldsa_back_lbe:
	s_waitcnt lgkmcnt(0)
	v_lshrrev_b32_e32 v124, v148, v124
	v_fmamk_f32 v34, v34, 0x3e38aa3b, v185
	v_fmamk_f32 v35, v35, 0x3e38aa3b, v185
	v_fmamk_f32 v36, v36, 0x3e38aa3b, v185
	v_fmamk_f32 v37, v37, 0x3e38aa3b, v185
	v_fmamk_f32 v38, v38, 0x3e38aa3b, v185
	v_fmamk_f32 v39, v39, 0x3e38aa3b, v185
	v_fmamk_f32 v40, v40, 0x3e38aa3b, v185
	v_fmamk_f32 v41, v41, 0x3e38aa3b, v185
	v_exp_f32_e32 v34, v34
	v_exp_f32_e32 v35, v35
	v_exp_f32_e32 v36, v36
	v_exp_f32_e32 v37, v37
	v_exp_f32_e32 v38, v38
	v_exp_f32_e32 v39, v39
	v_exp_f32_e32 v40, v40
	v_exp_f32_e32 v41, v41
	v_bfe_i32 v96, v124, 0, 1
	v_bfe_i32 v97, v124, 1, 1
	v_bfe_i32 v98, v124, 2, 1
	v_bfe_i32 v99, v124, 3, 1
	v_bfe_i32 v100, v124, 4, 1
	v_bfe_i32 v101, v124, 5, 1
	v_bfe_i32 v102, v124, 6, 1
	v_bfe_i32 v103, v124, 7, 1
	v_and_b32_e32 v34, v96, v34
	v_and_b32_e32 v35, v97, v35
	v_and_b32_e32 v36, v98, v36
	v_and_b32_e32 v37, v99, v37
	v_and_b32_e32 v38, v100, v38
	v_and_b32_e32 v39, v101, v39
	v_and_b32_e32 v40, v102, v40
	v_and_b32_e32 v41, v103, v41
	v_add_f32_e32 v123, v34, v35
	v_add_f32_e32 v123, v123, v36
	v_add_f32_e32 v123, v123, v37
	v_add_f32_e32 v123, v123, v38
	v_add_f32_e32 v123, v123, v39
	v_add_f32_e32 v123, v123, v40
	v_add_f32_e32 v123, v123, v41
	v_cvt_pk_bf16_f32 v88, v34, v35
	v_cvt_pk_bf16_f32 v89, v36, v37
	v_cvt_pk_bf16_f32 v90, v38, v39
	v_cvt_pk_bf16_f32 v91, v40, v41
	v_fmamk_f32 v42, v42, 0x3e38aa3b, v185
	v_fmamk_f32 v43, v43, 0x3e38aa3b, v185
	v_mfma_f32_32x32x16_bf16 v[18:33], v[104:107], v[88:91], v[18:33]
	v_fmamk_f32 v44, v44, 0x3e38aa3b, v185
	v_fmamk_f32 v45, v45, 0x3e38aa3b, v185
	v_fmamk_f32 v46, v46, 0x3e38aa3b, v185
	v_fmamk_f32 v47, v47, 0x3e38aa3b, v185
	v_fmamk_f32 v48, v48, 0x3e38aa3b, v185
	v_fmamk_f32 v49, v49, 0x3e38aa3b, v185
	v_exp_f32_e32 v42, v42
	v_exp_f32_e32 v43, v43
	v_exp_f32_e32 v44, v44
	v_exp_f32_e32 v45, v45
	v_exp_f32_e32 v46, v46
	v_exp_f32_e32 v47, v47
	v_mfma_f32_32x32x16_bf16 v[2:17], v[108:111], v[88:91], v[2:17]
	v_exp_f32_e32 v48, v48
	v_exp_f32_e32 v49, v49
	v_bfe_i32 v96, v124, 16, 1
	v_bfe_i32 v97, v124, 17, 1
	v_bfe_i32 v98, v124, 18, 1
	v_bfe_i32 v99, v124, 19, 1
	v_bfe_i32 v100, v124, 20, 1
	v_bfe_i32 v101, v124, 21, 1
	v_bfe_i32 v102, v124, 22, 1
	v_bfe_i32 v103, v124, 23, 1
	v_and_b32_e32 v42, v96, v42
	v_and_b32_e32 v43, v97, v43
	v_and_b32_e32 v44, v98, v44
	v_and_b32_e32 v45, v99, v45
	v_and_b32_e32 v46, v100, v46
	v_and_b32_e32 v47, v101, v47
	v_and_b32_e32 v48, v102, v48
	v_and_b32_e32 v49, v103, v49
	v_add_f32_e32 v123, v123, v42
	v_add_f32_e32 v123, v123, v43
	v_add_f32_e32 v123, v123, v44
	v_add_f32_e32 v123, v123, v45
	v_add_f32_e32 v123, v123, v46
	v_add_f32_e32 v123, v123, v47
	v_add_f32_e32 v123, v123, v48
	v_add_f32_e32 v123, v123, v49
	v_cvt_pk_bf16_f32 v92, v42, v43
	v_cvt_pk_bf16_f32 v93, v44, v45
	v_cvt_pk_bf16_f32 v94, v46, v47
	v_cvt_pk_bf16_f32 v95, v48, v49
	v_add_f32_e32 v141, v141, v123
	s_nop 0
	v_mfma_f32_32x32x16_bf16 v[18:33], v[112:115], v[92:95], v[18:33]
	v_mfma_f32_32x32x16_bf16 v[2:17], v[116:119], v[92:95], v[2:17]
	s_branch .Ldsa_next_e

.Ldsa_top_o:
	s_cmp_gt_i32 s65, s67
	s_cbranch_scc1 .Ldsa_next_o
	s_and_b32 s40, s65, 15
	s_lshl_b32 s40, s40, 13
	s_lshl_b32 s66, s65, 10
	s_and_b32 s66, s66, 0x3000
	s_and_b32 s41, s65, 3
	s_lshl_b32 s41, s41, 2
	s_add_i32 s66, s66, s41
	s_add_i32 s66, s66, 0x20020
	s_cmp_eq_u32 s65, s67
	s_cbranch_scc1 .Ldsa_last_o
	s_add_i32 s41, s65, 1
	s_and_b32 s41, s41, 15
	s_lshl_b32 s41, s41, 13
	v_add_u32_e32 v177, s41, v216
	ds_read_b128 v[66:69], v177
	v_add_u32_e32 v178, s41, v217
	ds_read_b128 v[70:73], v178
	v_add_u32_e32 v179, s41, v218
	ds_read_b128 v[74:77], v179
	v_add_u32_e32 v180, s41, v219
	ds_read_b128 v[78:81], v180
	ds_read_b128 v[104:107], v181 offset:12288
	ds_read_b128 v[108:111], v181 offset:14336
	ds_read_b128 v[112:115], v182 offset:12288
	ds_read_b128 v[116:119], v182 offset:14336
	ds_read_b32 v124, v183 offset:4
	v_max3_f32 v121, v200, v201, v202
	v_max3_f32 v121, v121, v203, v204
	v_max3_f32 v121, v121, v205, v206
	v_max3_f32 v121, v121, v207, v208
	v_max3_f32 v121, v121, v209, v210
	v_max3_f32 v121, v121, v211, v212
	v_max3_f32 v121, v121, v213, v214
	v_max_f32_e32 v121, v121, v215
	s_waitcnt lgkmcnt(5)
	v_mfma_f32_32x32x16_bf16 v[34:49], v[66:69], v[50:53], 0
	v_mov_b32_e32 v122, v121
	s_nop 1
	v_permlane32_swap_b32_e32 v121, v122
	v_max_f32_e32 v121, v121, v122
	v_mfma_f32_32x32x16_bf16 v[34:49], v[70:73], v[54:57], v[34:49]
	v_cmp_gt_f32_e32 vcc, v121, v184
	s_cbranch_vccnz .Ldsa_rare_fbo
.Ldsa_back_fbo:
	s_waitcnt lgkmcnt(0)
	v_lshrrev_b32_e32 v124, v148, v124
	v_fmamk_f32 v200, v200, 0x3e38aa3b, v185
	v_fmamk_f32 v201, v201, 0x3e38aa3b, v185
	v_fmamk_f32 v202, v202, 0x3e38aa3b, v185
	v_fmamk_f32 v203, v203, 0x3e38aa3b, v185
	v_fmamk_f32 v204, v204, 0x3e38aa3b, v185
	v_fmamk_f32 v205, v205, 0x3e38aa3b, v185
	v_fmamk_f32 v206, v206, 0x3e38aa3b, v185
	v_fmamk_f32 v207, v207, 0x3e38aa3b, v185
	v_mfma_f32_32x32x16_bf16 v[34:49], v[74:77], v[58:61], v[34:49]
	v_exp_f32_e32 v200, v200
	v_exp_f32_e32 v201, v201
	v_exp_f32_e32 v202, v202
	v_exp_f32_e32 v203, v203
	v_exp_f32_e32 v204, v204
	v_exp_f32_e32 v205, v205
	v_exp_f32_e32 v206, v206
	v_exp_f32_e32 v207, v207
	v_bfe_i32 v96, v124, 0, 1
	v_bfe_i32 v97, v124, 1, 1
	v_bfe_i32 v98, v124, 2, 1
	v_bfe_i32 v99, v124, 3, 1
	v_mfma_f32_32x32x16_bf16 v[34:49], v[78:81], v[62:65], v[34:49]
	v_bfe_i32 v100, v124, 4, 1
	v_bfe_i32 v101, v124, 5, 1
	v_bfe_i32 v102, v124, 6, 1
	v_bfe_i32 v103, v124, 7, 1
	v_and_b32_e32 v200, v96, v200
	v_and_b32_e32 v201, v97, v201
	v_and_b32_e32 v202, v98, v202
	v_and_b32_e32 v203, v99, v203
	v_and_b32_e32 v204, v100, v204
	v_and_b32_e32 v205, v101, v205
	v_and_b32_e32 v206, v102, v206
	v_and_b32_e32 v207, v103, v207
	v_add_f32_e32 v123, v200, v201
	v_add_f32_e32 v123, v123, v202
	v_add_f32_e32 v123, v123, v203
	v_add_f32_e32 v123, v123, v204
	v_add_f32_e32 v123, v123, v205
	v_add_f32_e32 v123, v123, v206
	v_add_f32_e32 v123, v123, v207
	v_cvt_pk_bf16_f32 v88, v200, v201
	v_cvt_pk_bf16_f32 v89, v202, v203
	v_cvt_pk_bf16_f32 v90, v204, v205
	v_cvt_pk_bf16_f32 v91, v206, v207
	v_fmamk_f32 v208, v208, 0x3e38aa3b, v185
	v_fmamk_f32 v209, v209, 0x3e38aa3b, v185
	v_mfma_f32_32x32x16_bf16 v[18:33], v[104:107], v[88:91], v[18:33]
	v_fmamk_f32 v210, v210, 0x3e38aa3b, v185
	v_fmamk_f32 v211, v211, 0x3e38aa3b, v185
	v_fmamk_f32 v212, v212, 0x3e38aa3b, v185
	v_fmamk_f32 v213, v213, 0x3e38aa3b, v185
	v_fmamk_f32 v214, v214, 0x3e38aa3b, v185
	v_fmamk_f32 v215, v215, 0x3e38aa3b, v185
	v_exp_f32_e32 v208, v208
	v_exp_f32_e32 v209, v209
	v_exp_f32_e32 v210, v210
	v_exp_f32_e32 v211, v211
	v_exp_f32_e32 v212, v212
	v_exp_f32_e32 v213, v213
	v_mfma_f32_32x32x16_bf16 v[2:17], v[108:111], v[88:91], v[2:17]
	v_exp_f32_e32 v214, v214
	v_exp_f32_e32 v215, v215
	v_bfe_i32 v96, v124, 16, 1
	v_bfe_i32 v97, v124, 17, 1
	v_bfe_i32 v98, v124, 18, 1
	v_bfe_i32 v99, v124, 19, 1
	v_bfe_i32 v100, v124, 20, 1
	v_bfe_i32 v101, v124, 21, 1
	v_bfe_i32 v102, v124, 22, 1
	v_bfe_i32 v103, v124, 23, 1
	v_and_b32_e32 v208, v96, v208
	v_and_b32_e32 v209, v97, v209
	v_and_b32_e32 v210, v98, v210
	v_and_b32_e32 v211, v99, v211
	v_and_b32_e32 v212, v100, v212
	v_and_b32_e32 v213, v101, v213
	v_and_b32_e32 v214, v102, v214
	v_and_b32_e32 v215, v103, v215
	v_add_f32_e32 v123, v123, v208
	v_add_f32_e32 v123, v123, v209
	v_add_f32_e32 v123, v123, v210
	v_add_f32_e32 v123, v123, v211
	v_add_f32_e32 v123, v123, v212
	v_add_f32_e32 v123, v123, v213
	v_add_f32_e32 v123, v123, v214
	v_add_f32_e32 v123, v123, v215
	v_cvt_pk_bf16_f32 v92, v208, v209
	v_cvt_pk_bf16_f32 v93, v210, v211
	v_cvt_pk_bf16_f32 v94, v212, v213
	v_cvt_pk_bf16_f32 v95, v214, v215
	v_add_f32_e32 v141, v141, v123
	s_nop 0
	v_mfma_f32_32x32x16_bf16 v[18:33], v[112:115], v[92:95], v[18:33]
	v_mfma_f32_32x32x16_bf16 v[2:17], v[116:119], v[92:95], v[2:17]
	s_branch .Ldsa_next_o
.Ldsa_last_o:
	ds_read_b128 v[104:107], v181 offset:12288
	ds_read_b128 v[108:111], v181 offset:14336
	ds_read_b128 v[112:115], v182 offset:12288
	ds_read_b128 v[116:119], v182 offset:14336
	ds_read_b32 v124, v183 offset:4
	v_max3_f32 v121, v200, v201, v202
	v_max3_f32 v121, v121, v203, v204
	v_max3_f32 v121, v121, v205, v206
	v_max3_f32 v121, v121, v207, v208
	v_max3_f32 v121, v121, v209, v210
	v_max3_f32 v121, v121, v211, v212
	v_max3_f32 v121, v121, v213, v214
	v_max_f32_e32 v121, v121, v215
	v_mov_b32_e32 v122, v121
	s_nop 1
	v_permlane32_swap_b32_e32 v121, v122
	v_max_f32_e32 v121, v121, v122
	v_cmp_gt_f32_e32 vcc, v121, v184
	s_cbranch_vccnz .Ldsa_rare_lbo
.Ldsa_back_lbo:
	s_waitcnt lgkmcnt(0)
	v_lshrrev_b32_e32 v124, v148, v124
	v_fmamk_f32 v200, v200, 0x3e38aa3b, v185
	v_fmamk_f32 v201, v201, 0x3e38aa3b, v185
	v_fmamk_f32 v202, v202, 0x3e38aa3b, v185
	v_fmamk_f32 v203, v203, 0x3e38aa3b, v185
	v_fmamk_f32 v204, v204, 0x3e38aa3b, v185
	v_fmamk_f32 v205, v205, 0x3e38aa3b, v185
	v_fmamk_f32 v206, v206, 0x3e38aa3b, v185
	v_fmamk_f32 v207, v207, 0x3e38aa3b, v185
	v_exp_f32_e32 v200, v200
	v_exp_f32_e32 v201, v201
	v_exp_f32_e32 v202, v202
	v_exp_f32_e32 v203, v203
	v_exp_f32_e32 v204, v204
	v_exp_f32_e32 v205, v205
	v_exp_f32_e32 v206, v206
	v_exp_f32_e32 v207, v207
	v_bfe_i32 v96, v124, 0, 1
	v_bfe_i32 v97, v124, 1, 1
	v_bfe_i32 v98, v124, 2, 1
	v_bfe_i32 v99, v124, 3, 1
	v_bfe_i32 v100, v124, 4, 1
	v_bfe_i32 v101, v124, 5, 1
	v_bfe_i32 v102, v124, 6, 1
	v_bfe_i32 v103, v124, 7, 1
	v_and_b32_e32 v200, v96, v200
	v_and_b32_e32 v201, v97, v201
	v_and_b32_e32 v202, v98, v202
	v_and_b32_e32 v203, v99, v203
	v_and_b32_e32 v204, v100, v204
	v_and_b32_e32 v205, v101, v205
	v_and_b32_e32 v206, v102, v206
	v_and_b32_e32 v207, v103, v207
	v_add_f32_e32 v123, v200, v201
	v_add_f32_e32 v123, v123, v202
	v_add_f32_e32 v123, v123, v203
	v_add_f32_e32 v123, v123, v204
	v_add_f32_e32 v123, v123, v205
	v_add_f32_e32 v123, v123, v206
	v_add_f32_e32 v123, v123, v207
	v_cvt_pk_bf16_f32 v88, v200, v201
	v_cvt_pk_bf16_f32 v89, v202, v203
	v_cvt_pk_bf16_f32 v90, v204, v205
	v_cvt_pk_bf16_f32 v91, v206, v207
	v_fmamk_f32 v208, v208, 0x3e38aa3b, v185
	v_fmamk_f32 v209, v209, 0x3e38aa3b, v185
	v_mfma_f32_32x32x16_bf16 v[18:33], v[104:107], v[88:91], v[18:33]
	v_fmamk_f32 v210, v210, 0x3e38aa3b, v185
	v_fmamk_f32 v211, v211, 0x3e38aa3b, v185
	v_fmamk_f32 v212, v212, 0x3e38aa3b, v185
	v_fmamk_f32 v213, v213, 0x3e38aa3b, v185
	v_fmamk_f32 v214, v214, 0x3e38aa3b, v185
	v_fmamk_f32 v215, v215, 0x3e38aa3b, v185
	v_exp_f32_e32 v208, v208
	v_exp_f32_e32 v209, v209
	v_exp_f32_e32 v210, v210
	v_exp_f32_e32 v211, v211
	v_exp_f32_e32 v212, v212
	v_exp_f32_e32 v213, v213
	v_mfma_f32_32x32x16_bf16 v[2:17], v[108:111], v[88:91], v[2:17]
	v_exp_f32_e32 v214, v214
	v_exp_f32_e32 v215, v215
	v_bfe_i32 v96, v124, 16, 1
	v_bfe_i32 v97, v124, 17, 1
	v_bfe_i32 v98, v124, 18, 1
	v_bfe_i32 v99, v124, 19, 1
	v_bfe_i32 v100, v124, 20, 1
	v_bfe_i32 v101, v124, 21, 1
	v_bfe_i32 v102, v124, 22, 1
	v_bfe_i32 v103, v124, 23, 1
	v_and_b32_e32 v208, v96, v208
	v_and_b32_e32 v209, v97, v209
	v_and_b32_e32 v210, v98, v210
	v_and_b32_e32 v211, v99, v211
	v_and_b32_e32 v212, v100, v212
	v_and_b32_e32 v213, v101, v213
	v_and_b32_e32 v214, v102, v214
	v_and_b32_e32 v215, v103, v215
	v_add_f32_e32 v123, v123, v208
	v_add_f32_e32 v123, v123, v209
	v_add_f32_e32 v123, v123, v210
	v_add_f32_e32 v123, v123, v211
	v_add_f32_e32 v123, v123, v212
	v_add_f32_e32 v123, v123, v213
	v_add_f32_e32 v123, v123, v214
	v_add_f32_e32 v123, v123, v215
	v_cvt_pk_bf16_f32 v92, v208, v209
	v_cvt_pk_bf16_f32 v93, v210, v211
	v_cvt_pk_bf16_f32 v94, v212, v213
	v_cvt_pk_bf16_f32 v95, v214, v215
	v_add_f32_e32 v141, v141, v123
	s_nop 0
	v_mfma_f32_32x32x16_bf16 v[18:33], v[112:115], v[92:95], v[18:33]
	v_mfma_f32_32x32x16_bf16 v[2:17], v[116:119], v[92:95], v[2:17]
	s_branch .Ldsa_next_o

.Ldsa_rare_fbe:
	s_nop 15
	s_nop 15
	v_cndmask_b32_e32 v122, v83, v121, vcc
	v_sub_f32_e32 v126, v83, v122
	v_mul_f32_e32 v126, 0x3e38aa3b, v126
	v_exp_f32_e32 v126, v126
	v_mov_b32_e32 v83, v122
	v_add_f32_e32 v184, 0x42317218, v122
	v_mul_f32_e32 v185, 0xbe38aa3b, v122
	v_mul_f32_e32 v141, v141, v126
	v_pk_mul_f32 v[32:33], v[32:33], v[126:127] op_sel_hi:[1,0]
	v_pk_mul_f32 v[30:31], v[30:31], v[126:127] op_sel_hi:[1,0]
	v_pk_mul_f32 v[28:29], v[28:29], v[126:127] op_sel_hi:[1,0]
	v_pk_mul_f32 v[26:27], v[26:27], v[126:127] op_sel_hi:[1,0]
	v_pk_mul_f32 v[24:25], v[24:25], v[126:127] op_sel_hi:[1,0]
	v_pk_mul_f32 v[22:23], v[22:23], v[126:127] op_sel_hi:[1,0]
	v_pk_mul_f32 v[20:21], v[20:21], v[126:127] op_sel_hi:[1,0]
	v_pk_mul_f32 v[18:19], v[18:19], v[126:127] op_sel_hi:[1,0]
	v_pk_mul_f32 v[16:17], v[16:17], v[126:127] op_sel_hi:[1,0]
	v_pk_mul_f32 v[14:15], v[14:15], v[126:127] op_sel_hi:[1,0]
	v_pk_mul_f32 v[12:13], v[12:13], v[126:127] op_sel_hi:[1,0]
	v_pk_mul_f32 v[10:11], v[10:11], v[126:127] op_sel_hi:[1,0]
	v_pk_mul_f32 v[8:9], v[8:9], v[126:127] op_sel_hi:[1,0]
	v_pk_mul_f32 v[6:7], v[6:7], v[126:127] op_sel_hi:[1,0]
	v_pk_mul_f32 v[4:5], v[4:5], v[126:127] op_sel_hi:[1,0]
	v_pk_mul_f32 v[2:3], v[2:3], v[126:127] op_sel_hi:[1,0]
	s_branch .Ldsa_back_fbe

.Ldil_top:
	s_cmp_eq_u32 s41, 2
	s_cbranch_scc1 .Ldil_nb
	s_barrier
